# grid barrier: the per-CU L1 invalidate is issued right after arrival (no cached loads happen until release), so it overlaps the wait
# speedup vs baseline: 1.0380x; 1.0045x over previous
; __global__ void __launch_bounds__(512) mega(Params P) {
;     ...
;   grid.sync();
.Lgbx_arr_0:
	s_lshl_b32 s1, s1, 2
	s_addk_i32 s1, 0x88
	v_mov_b32_e32 v2, s1
	global_load_dword v0, v1, s[4:5] sc1
	v_mov_b32_e32 v3, 1
	s_waitcnt vmcnt(0)
	v_and_b32_e32 v0, 0xffff0000, v0
	global_atomic_add v3, v2, v3, s[4:5] sc0
	s_waitcnt vmcnt(0)
	buffer_inv sc1
	v_and_b32_e32 v3, 0xffff, v3
	s_nop 0
	v_readfirstlane_b32 s1, v3
	s_nop 3
	s_add_i32 s0, s6, -1
	s_cmp_lg_u32 s1, s0
	s_cbranch_scc1 .Lgbx_poll_0
	s_cmp_eq_u32 s96, 0
	s_cbranch_scc0 .Lgbx_nofl_0
	buffer_wbl2 sc1
	s_waitcnt vmcnt(0)

; __global__ void __launch_bounds__(512) mega(Params P) {
;     ...
;   grid.sync();
.Lgb_done_0:
.LBB0_235:
	s_or_b64 exec, exec, s[2:3]
	s_barrier

; #define LAS __attribute__((address_space(3)))
; __device__ __forceinline__ int ltid() { return launder((int)threadIdx.x); }
; __device__ __forceinline__ float bf2f(unsigned short b) { return __uint_as_float(((unsigned)b) << 16); }
; template <int M> __device__ __forceinline__ float shx(float v) { return __builtin_bit_cast(float, __builtin_amdgcn_ds_swizzle(__builtin_bit_cast(int, v), (M << 10) | 0x1f)); }
; template <class Epi, class Pre>
; __device__ __forceinline__ void meta_gemm(const bf16_t* __restrict__ A, int lda, const bf16_t* __restrict__ Bt, int ldb, int N, int K, Epi& epi, Pre pre) {
;   const int tid = ltid(), wid = tid >> 6, lane = tid & 63, fr = lane & 15, fq = lane >> 4;
;   LAS float* part = (LAS float*)lds_raw;
;   const int nunits = N / 64, ks = K / 8;
;   for (int u = blockIdx.x; u < nunits; u += gridDim.x) {
;     const int cb = (u >> 2) * 256 + (u & 3) * 32;
;     f32x4 acc[2][2];
; #pragma unroll
;     for (int bj = 0; bj < 2; ++bj)
; #pragma unroll
;       for (int n = 0; n < 2; ++n) acc[bj][n] = (f32x4){0.f, 0.f, 0.f, 0.f};
;     const bf16_t* ap = A + (size_t)(NREAL + fr) * lda + wid * ks + fq * 8;
;     const bf16_t* bp = Bt + (size_t)(cb + fr) * ldb + wid * ks + fq * 8;
; __device__ __forceinline__ void up_phase(const bf16_t* cqkv, const bf16_t* wqb, const bf16_t* wkvb, EpiUp& epi) {
;     ...
;     epi.use_direct = 1;
;     auto preq = [&](int fr, int fq) { const bf16_t* p = cqkv + (size_t)(NREAL + fr) * 512 + fq * 64; float ss = 0.f;
; #pragma unroll
;       for (int c = 0; c < 8; ++c) { const u32x4 w = *(const u32x4*)(p + c * 8);
; #pragma unroll
;         for (int q = 0; q < 4; ++q) { const float a = bf2f(w[q] & 0xffff), b = bf2f(w[q] >> 16); ss += a * a + b * b; } }
;       ss += shx<16>(ss); ss = sum32(ss); epi.rs_direct = rsqrtf(ss * (1.0f / 256.0f) + 1e-6f); };
;     auto prekv = [&](int fr, int fq) { const bf16_t* p = cqkv + (size_t)(NREAL + fr) * 512 + 256 + fq * 32; float ss = 0.f;
; #pragma unroll
;       for (int c = 0; c < 4; ++c) { const u32x4 w = *(const u32x4*)(p + c * 8);
; #pragma unroll
;         for (int q = 0; q < 4; ++q) { const float a = bf2f(w[q] & 0xffff), b = bf2f(w[q] >> 16); ss += a * a + b * b; } }
;       ss += shx<16>(ss); ss = sum32(ss); epi.rs_direct = rsqrtf(ss * (1.0f / 128.0f) + 1e-6f); };
;     meta_gemm(cqkv, 512, wqb, 256, 768, 256, epi, preq);
.Lgb_done_1:
.LBB0_779:
	s_or_b64 exec, exec, s[2:3]
	s_xor_b64 s[0:1], s[60:61], -1
	v_writelane_b32 v254, s0, 56
	v_mov_b32_e32 v27, v155
	v_mov_b32_e32 v0, v155
	v_writelane_b32 v254, s1, 57
	s_barrier
	v_readlane_b32 s0, v254, 54
	s_mul_i32 s90, s0, 0x30000
	s_lshl_b64 s[6:7], s[90:91], 1
	v_readlane_b32 s0, v253, 43
	v_readlane_b32 s1, v254, 55
	s_add_u32 s34, s0, s6
	v_readlane_b32 s0, v253, 44
	s_addc_u32 s35, s0, s7
	v_readlane_b32 s0, v254, 28
	v_readlane_b32 s1, v254, 29
	s_andn2_b64 vcc, exec, s[0:1]
	s_nop 0
	v_cndmask_b32_e64 v2, 0, 1, s[0:1]
	v_cmp_ne_u32_e64 s[2:3], 1, v2
	s_cbranch_vccnz .LBB0_807
	v_and_b32_e32 v110, 15, v0
	v_readlane_b32 s0, v254, 0
	v_lshlrev_b32_e32 v2, 10, v110
	v_mov_b32_e32 v3, v1
	v_readlane_b32 s1, v254, 1
	v_ashrrev_i32_e32 v12, 6, v0
	v_and_b32_e32 v10, 48, v0
	v_lshl_add_u64 v[2:3], s[0:1], 0, v[2:3]
	s_mov_b64 s[0:1], 0x2000000
	v_lshl_add_u64 v[6:7], v[2:3], 0, s[0:1]
	v_lshlrev_b32_e32 v2, 5, v12
	v_ashrrev_i32_e32 v3, 31, v2
	v_lshlrev_b64 v[8:9], 1, v[2:3]
	v_lshl_add_u64 v[2:3], v[6:7], 0, v[8:9]
	v_mov_b32_e32 v11, v1
	v_lshl_add_u64 v[2:3], v[2:3], 0, v[10:11]
	global_load_dwordx4 v[2:5], v[2:3], off
	v_lshl_add_u64 v[8:9], s[34:35], 0, v[8:9]
	v_lshl_add_u64 v[22:23], v[8:9], 0, v[10:11]
	v_lshl_add_u32 v8, v12, 4, v211
	s_movk_i32 s0, 0x1fff
	v_or_b32_e32 v9, v8, v110
	v_ashrrev_i32_e32 v10, 13, v8
	v_bitop3_b32 v8, v8, s0, v110 bitop3:0xc8
	s_mov_b32 s0, 0x8000
	v_bfe_u32 v14, v0, 4, 2
	v_add_u32_e32 v8, 64, v8
	v_and_b32_e32 v11, 3, v12
	v_cmp_gt_i32_e32 vcc, s0, v9
	v_readlane_b32 s0, v254, 26
	v_readlane_b32 s1, v254, 27
	v_cndmask_b32_e32 v9, v11, v10, vcc
	v_cndmask_b32_e32 v24, v110, v8, vcc
	v_lshlrev_b32_e32 v10, 7, v14
	v_mov_b32_e32 v11, v1
	v_lshlrev_b32_e32 v8, 4, v24
	v_lshl_add_u64 v[28:29], v[6:7], 0, v[10:11]
	v_lshlrev_b32_e32 v6, 1, v24
	v_mov_b32_e32 v7, v1
	v_mul_i32_i24_e32 v112, 6, v9
	v_add_u32_e32 v9, 0xfffffd00, v8
	v_lshl_add_u64 v[30:31], s[0:1], 0, v[6:7]
	v_readlane_b32 s0, v253, 40
	v_and_b32_e32 v13, 63, v0
	v_cndmask_b32_e32 v8, v8, v9, vcc
	v_mov_b32_e32 v9, v1
	v_readlane_b32 s1, v253, 41
	v_lshl_add_u32 v111, v13, 2, 0
	v_cmp_gt_i32_e64 s[4:5], 4, v12
	v_lshlrev_b32_e32 v12, 12, v12
	v_lshl_add_u64 v[6:7], v[8:9], 3, s[0:1]
	v_lshlrev_b32_e32 v8, 5, v14
	v_lshlrev_b32_e32 v0, 3, v14
	v_lshlrev_b32_e32 v26, 2, v14
	v_mov_b32_e32 v25, v1
	v_lshl_add_u64 v[32:33], v[6:7], 0, v[8:9]
	v_add_u32_e32 v113, v111, v12
	v_readlane_b32 s0, v254, 36
	v_readlane_b32 s1, v254, 45
	s_mov_b32 s12, s48
	s_branch .LBB0_782

; #define LAS __attribute__((address_space(3)))
; __device__ __forceinline__ int ltid() { return launder((int)threadIdx.x); }
; __device__ __forceinline__ float sum32(float v) { return v + xhalf(v); }
; template <int MODE>
; __device__ __forceinline__ void attn_item(const Params& P, int layer, int b, int h, int map, int qb) {
;     ...
;       const float lam = ((const float*)(ws + WS_CTL))[8 + layer], li = layer == 0 ? 0.2f : 0.35550906f, ib = lam * ia;
;       f32x16 y0, y1; float ss = 0.f;
; #pragma unroll
;       for (int i = 0; i < 16; ++i) { y0[i] = stash[i * 64] - sa.o0[i] * ib; y1[i] = stash[(16 + i) * 64] - sa.o1[i] * ib; ss += y0[i] * y0[i] + y1[i] * y1[i]; }
;       ss = sum32(ss);
;       const float rs = rsqrtf(ss * (1.0f / 64.0f) + 1e-6f) * (1.0f - li);
;       const float* sg = P.subln + layer * 64 + 4 * hh;
; __device__ __forceinline__ void attn_phase(const Params& P, int layer) {
;   unsigned* ctl = (unsigned*)(P.ws + WS_CTL);
;   LAS volatile int* slot = (LAS volatile int*)(lds_raw + SLOT_OFF);
;   const int xcd = blockIdx.x & 7;
;   for (int probe = 0; probe < 8; ++probe) {
;     const int q = (xcd + probe) & 7;
;     for (;;) {
;       __syncthreads();
;       if (ltid() == 0) *slot = (int)atomicAdd(ctl + 16 + layer * 8 + q, 1u);
.Lgb_done_2:
.LBB0_1217:
	s_or_b64 exec, exec, s[2:3]
	v_readlane_b32 s4, v253, 16
	v_readlane_b32 s12, v254, 54
	v_readlane_b32 s5, v253, 17
	v_readlane_b32 s6, v253, 18
	v_readlane_b32 s7, v253, 19
	v_readlane_b32 s8, v253, 20
	v_readlane_b32 s9, v253, 21
	s_lshl_b32 s90, s12, 3
	v_readlane_b32 s10, v253, 22
	v_readlane_b32 s11, v253, 23
	s_mov_b64 s[4:5], s[8:9]
	s_lshl_b64 s[0:1], s[90:91], 2
	s_mov_b64 s[6:7], s[10:11]
	s_add_u32 s0, s6, s0
	v_readlane_b32 s13, v254, 55
	v_writelane_b32 v254, s0, 58
	s_addc_u32 s0, s7, s1
	v_writelane_b32 v254, s0, 59
	s_lshl_b32 s90, s12, 6
	s_lshl_b64 s[0:1], s[12:13], 2
	s_add_u32 s52, s6, s0
	s_addc_u32 s53, s7, s1
	v_readlane_b32 s0, v253, 0
	s_lshl_b64 s[16:17], s[90:91], 2
	v_readlane_b32 s4, v253, 4
	v_mov_b32_e32 v0, 0x3f24fd5c
	v_mov_b32_e32 v2, 0x3f4ccccd
	v_readlane_b32 s5, v253, 5
	s_add_u32 s56, s4, s16
	v_cndmask_b32_e64 v220, v0, v2, s[60:61]
	s_addc_u32 s57, s5, s17
	s_mov_b32 s0, 0
	s_barrier
	v_readlane_b32 s1, v253, 1
	v_readlane_b32 s2, v253, 2
	v_readlane_b32 s3, v253, 3
	v_readlane_b32 s6, v253, 6
	v_readlane_b32 s7, v253, 7
	v_readlane_b32 s8, v253, 8
	v_readlane_b32 s9, v253, 9
	v_readlane_b32 s10, v253, 10
	v_readlane_b32 s11, v253, 11
	v_readlane_b32 s12, v253, 12
	v_readlane_b32 s13, v253, 13
	v_readlane_b32 s14, v253, 14
	v_readlane_b32 s15, v253, 15
	s_branch .LBB0_1219

; #define LAS __attribute__((address_space(3)))
; __device__ __forceinline__ int ltid() { return launder((int)threadIdx.x); }
; template <class Epi, class Pre>
; __device__ __forceinline__ void meta_gemm(const bf16_t* __restrict__ A, int lda, const bf16_t* __restrict__ Bt, int ldb, int N, int K, Epi& epi, Pre pre) {
;   const int tid = ltid(), wid = tid >> 6, lane = tid & 63, fr = lane & 15, fq = lane >> 4;
;   LAS float* part = (LAS float*)lds_raw;
;   const int nunits = N / 64, ks = K / 8;
;   for (int u = blockIdx.x; u < nunits; u += gridDim.x) {
;     const int cb = (u >> 2) * 256 + (u & 3) * 32;
;     f32x4 acc[2][2];
; #pragma unroll
;     for (int bj = 0; bj < 2; ++bj)
; #pragma unroll
;       for (int n = 0; n < 2; ++n) acc[bj][n] = (f32x4){0.f, 0.f, 0.f, 0.f};
;     const bf16_t* ap = A + (size_t)(NREAL + fr) * lda + wid * ks + fq * 8;
;     const bf16_t* bp = Bt + (size_t)(cb + fr) * ldb + wid * ks + fq * 8;
; __global__ void __launch_bounds__(512) mega(Params P) {
;     ...
;     if (l == 0) { EpiResid0 e; e.H = H; e.xsrc = P.x; e.msrc = P.meta; gemm_phase(HN, DM, (const bf16_t*)(ws + WS_WOUT), 1024, NREAL, 1024, 1024, e); }
;     else { EpiResid e; e.H = H; gemm_phase(HN, DM, (const bf16_t*)(ws + WS_WOUT) + (size_t)l * 1024 * 1024, 1024, NREAL, 1024, 1024, e); }
.Lgb_done_3:
.LBB0_1442:
	s_or_b64 exec, exec, s[2:3]
	v_readlane_b32 s0, v254, 56
	v_readlane_b32 s1, v254, 57
	s_and_b64 vcc, exec, s[0:1]
	v_readlane_b32 s0, v254, 32
	v_readlane_b32 s1, v254, 33
	s_mov_b64 s[4:5], -1
	s_barrier
	v_cndmask_b32_e64 v0, 0, 1, s[0:1]
	v_cmp_ne_u32_e64 s[2:3], 1, v0
	s_cbranch_vccz .LBB0_1466
	v_readlane_b32 s0, v254, 54
	v_readlane_b32 s1, v254, 55
	s_lshl_b64 s[6:7], s[0:1], 21
	v_readlane_b32 s0, v253, 51
	v_readlane_b32 s1, v253, 52
	s_add_u32 s8, s0, s6
	s_addc_u32 s9, s1, s7
	v_mov_b32_e32 v2, v155
	s_and_b64 vcc, exec, s[2:3]
	s_cbranch_vccnz .LBB0_1448
	v_and_b32_e32 v0, 15, v2
	v_ashrrev_i32_e32 v10, 6, v2
	v_or_b32_e32 v8, 0x8000, v0
	v_readlane_b32 s0, v253, 62
	v_lshlrev_b32_e32 v6, 7, v10
	v_lshlrev_b32_e32 v4, 11, v8
	v_mov_b32_e32 v5, v1
	v_readlane_b32 s1, v253, 63
	v_ashrrev_i32_e32 v7, 31, v6
	v_lshlrev_b64 v[6:7], 1, v[6:7]
	v_lshl_add_u64 v[4:5], s[0:1], 0, v[4:5]
	v_and_b32_e32 v9, 63, v2
	v_lshl_add_u64 v[4:5], v[4:5], 0, v[6:7]
	v_and_b32_e32 v2, 48, v2
	v_mov_b32_e32 v3, v1
	v_lshl_add_u64 v[18:19], v[4:5], 0, v[2:3]
	v_lshl_add_u64 v[4:5], s[8:9], 0, v[6:7]
	v_lshl_add_u64 v[20:21], v[4:5], 0, v[2:3]
	v_lshl_add_u32 v4, v10, 4, v8
	v_ashrrev_i32_e32 v5, 31, v4
	v_readlane_b32 s0, v253, 60
	v_lshlrev_b64 v[4:5], 12, v[4:5]
	v_readlane_b32 s1, v253, 61
	v_lshl_add_u32 v42, v9, 2, 0
	v_lshlrev_b32_e32 v6, 12, v10
	v_lshl_add_u64 v[4:5], s[0:1], 0, v[4:5]
	v_cmp_gt_i32_e64 s[4:5], 4, v10
	v_lshl_add_u64 v[22:23], v[4:5], 0, v[2:3]
	v_add_u32_e32 v43, v42, v6
	v_readlane_b32 s0, v254, 36
	v_readlane_b32 s1, v254, 45
	s_mov_b32 s14, s48
	s_branch .LBB0_1446

; __global__ void __launch_bounds__(512) mega(Params P) {
;     ...
;     grid.sync();
.Lgbx_arr_4:
	s_lshl_b32 s1, s1, 2
	s_addk_i32 s1, 0x88
	v_mov_b32_e32 v2, s1
	global_load_dword v0, v1, s[6:7] sc1
	v_mov_b32_e32 v3, 1
	s_waitcnt vmcnt(0)
	v_and_b32_e32 v0, 0xffff0000, v0
	global_atomic_add v3, v2, v3, s[6:7] sc0
	s_waitcnt vmcnt(0)
	buffer_inv sc1
	v_and_b32_e32 v3, 0xffff, v3
	s_nop 0
	v_readfirstlane_b32 s1, v3
	s_nop 3
	s_add_i32 s0, s8, -1
	s_cmp_lg_u32 s1, s0
	s_cbranch_scc1 .Lgbx_poll_4
	s_cmp_eq_u32 s96, 0
	s_cbranch_scc0 .Lgbx_nofl_4
	buffer_wbl2 sc1
	s_waitcnt vmcnt(0)

; __device__ __forceinline__ int ltid() { return launder((int)threadIdx.x); }
; __device__ __forceinline__ void norm_phase(const float* H, const float* g, bf16_t* HN) {
;   const int lane = ltid() & 63, gw = blockIdx.x * 8 + (ltid() >> 6), nw = gridDim.x * 8;
;   f32x4 gv[4];
; #pragma unroll
;   for (int i = 0; i < 4; ++i) gv[i] = *(const f32x4*)(g + lane * 8 + 512 * (i >> 1) + 4 * (i & 1));
;   for (int row = gw; row < NREAL + 64; row += 2 * nw) {
;     const int row2 = row + nw < NREAL + 64 ? row + nw : row;
;     const float* p = H + (size_t)row * DM + lane * 8; const float* p2 = H + (size_t)row2 * DM + lane * 8; f32x4 v[4], u[4]; float ss = 0.f, ss2 = 0.f;
; #pragma unroll
;     for (int i = 0; i < 4; ++i) { v[i] = *(const f32x4*)(p + 512 * (i >> 1) + 4 * (i & 1)); u[i] = *(const f32x4*)(p2 + 512 * (i >> 1) + 4 * (i & 1)); }
.Lgb_done_4:
.LBB0_1499:
	s_or_b64 exec, exec, s[4:5]
	v_mov_b32_e32 v0, v155
	v_mov_b32_e32 v2, v155
	s_barrier
	v_readlane_b32 s0, v253, 56
	v_ashrrev_i32_e32 v2, 6, v2
	s_nop 0
	v_add_u32_e32 v54, s0, v2
	v_cmp_gt_i32_e32 vcc, s49, v54
	s_and_saveexec_b64 s[6:7], vcc
	v_readlane_b32 s24, v253, 59
	s_cbranch_execz .LBB0_1502
	v_readlane_b32 s0, v254, 54
	v_readlane_b32 s8, v253, 0
	v_readlane_b32 s1, v254, 55
	s_lshl_b32 s90, s0, 10
	v_readlane_b32 s14, v253, 6
	v_readlane_b32 s15, v253, 7
	v_readlane_b32 s18, v253, 10
	v_readlane_b32 s19, v253, 11
	s_lshl_b64 s[0:1], s[90:91], 2
	s_mov_b64 s[14:15], s[18:19]
	v_lshlrev_b32_e32 v0, 2, v0
	s_add_u32 s0, s14, s0
	v_and_b32_e32 v0, 0xfc, v0
	s_addc_u32 s1, s15, s1
	v_lshlrev_b32_e32 v18, 2, v0
	global_load_dwordx4 v[2:5], v18, s[0:1]
	global_load_dwordx4 v[6:9], v18, s[0:1] offset:1024
	global_load_dwordx4 v[10:13], v18, s[0:1] offset:2048
	global_load_dwordx4 v[14:17], v18, s[0:1] offset:3072
	v_readlane_b32 s0, v253, 60
	v_mov_b32_e32 v19, v1
	v_readlane_b32 s1, v253, 61
	v_readlane_b32 s9, v253, 1
	s_mov_b64 s[8:9], 0
	v_lshl_add_u64 v[50:51], s[0:1], 0, v[18:19]
	v_readlane_b32 s0, v253, 62
	v_lshlrev_b32_e32 v18, 1, v0
	v_readlane_b32 s1, v253, 63
	v_readlane_b32 s10, v253, 2
	v_readlane_b32 s11, v253, 3
	v_lshl_add_u64 v[52:53], s[0:1], 0, v[18:19]
	v_readlane_b32 s12, v253, 4
	v_readlane_b32 s13, v253, 5
	v_readlane_b32 s16, v253, 8
	v_readlane_b32 s17, v253, 9
	v_readlane_b32 s20, v253, 12
	v_readlane_b32 s21, v253, 13
	v_readlane_b32 s22, v253, 14
	v_readlane_b32 s23, v253, 15

; #define LAS __attribute__((address_space(3)))
; __device__ __forceinline__ int ltid() { return launder((int)threadIdx.x); }
; template <class Epi, class Pre>
; __device__ __forceinline__ void meta_gemm(const bf16_t* __restrict__ A, int lda, const bf16_t* __restrict__ Bt, int ldb, int N, int K, Epi& epi, Pre pre) {
;   const int tid = ltid(), wid = tid >> 6, lane = tid & 63, fr = lane & 15, fq = lane >> 4;
;   LAS float* part = (LAS float*)lds_raw;
;   const int nunits = N / 64, ks = K / 8;
;   for (int u = blockIdx.x; u < nunits; u += gridDim.x) {
;     const int cb = (u >> 2) * 256 + (u & 3) * 32;
;     f32x4 acc[2][2];
; #pragma unroll
;     for (int bj = 0; bj < 2; ++bj)
; #pragma unroll
;       for (int n = 0; n < 2; ++n) acc[bj][n] = (f32x4){0.f, 0.f, 0.f, 0.f};
;     const bf16_t* ap = A + (size_t)(NREAL + fr) * lda + wid * ks + fq * 8;
;     const bf16_t* bp = Bt + (size_t)(cb + fr) * ldb + wid * ks + fq * 8;
; #pragma unroll 4
;     for (int k0 = 0; k0 < ks; k0 += 32) {
;       const bf16x8 a = *(const bf16x8*)(ap + k0);
; #pragma unroll
;       for (int bj = 0; bj < 2; ++bj)
; #pragma unroll
;         for (int n = 0; n < 2; ++n) { const bf16x8 b = *(const bf16x8*)(bp + (size_t)(bj * 128 + n * 16) * ldb + k0); acc[bj][n] = __builtin_amdgcn_mfma_f32_16x16x32_bf16(b, a, acc[bj][n], 0, 0, 0); }
;     }
; __global__ void __launch_bounds__(512) mega(Params P) {
;     ...
;     if (EN & 128) { EpiGU e; e.act = (bf16_t*)(ws + WS_ACT); gemm_phase(HN, DM, (const bf16_t*)(ws + WS_WGU) + (size_t)l * N_GU * 1024, 1024, NREAL, N_GU, 1024, e); }
.Lgb_done_5:
.LBB0_1512:
	s_or_b64 exec, exec, s[4:5]
	v_readlane_b32 s0, v254, 54
	v_readlane_b32 s1, v254, 55
	s_mul_i32 s0, s0, 0xb00000
	v_readlane_b32 s1, v253, 47
	v_readlane_b32 s4, v254, 39
	s_add_u32 s8, s1, s0
	v_readlane_b32 s1, v253, 48
	v_readlane_b32 s5, v254, 40
	s_addc_u32 s9, s1, 0
	v_mov_b32_e32 v18, v155
	s_andn2_b64 vcc, exec, s[4:5]
	s_barrier
	s_cbranch_vccnz .LBB0_1517
	v_ashrrev_i32_e32 v23, 6, v18
	v_lshlrev_b32_e32 v4, 7, v23
	v_and_b32_e32 v0, 15, v18
	v_readlane_b32 s4, v253, 62
	v_ashrrev_i32_e32 v5, 31, v4
	v_lshlrev_b32_e32 v2, 11, v0
	v_mov_b32_e32 v3, v1
	v_readlane_b32 s5, v253, 63
	v_lshlrev_b64 v[20:21], 1, v[4:5]
	v_lshrrev_b32_e32 v4, 1, v18
	v_lshl_add_u64 v[2:3], s[4:5], 0, v[2:3]
	v_and_b32_e32 v22, 24, v4
	v_lshl_add_u64 v[2:3], v[2:3], 0, v[20:21]
	v_lshlrev_b32_e32 v24, 1, v22
	v_mov_b32_e32 v25, v1
	v_lshl_add_u64 v[2:3], v[2:3], 0, v[24:25]
	s_mov_b64 s[4:5], 0x4000000
	v_add_co_u32_e32 v10, vcc, 0x4000000, v2
	v_lshl_add_u64 v[14:15], v[2:3], 0, s[4:5]
	s_nop 0
	v_addc_co_u32_e32 v11, vcc, 0, v3, vcc
	global_load_dwordx4 v[2:5], v[14:15], off offset:64
	global_load_dwordx4 v[6:9], v[14:15], off offset:128
	s_nop 0
	global_load_dwordx4 v[10:13], v[10:11], off
	s_nop 0
	global_load_dwordx4 v[14:17], v[14:15], off offset:192
	v_readlane_b32 s6, v254, 24
	v_and_b32_e32 v26, 63, v18
	v_lshl_add_u64 v[18:19], s[8:9], 0, v[20:21]
	v_lshl_or_b32 v20, v23, 4, v0
	v_readlane_b32 s7, v254, 25
	v_lshl_add_u64 v[18:19], v[18:19], 0, v[24:25]
	v_lshl_add_u32 v74, v26, 2, 0
	v_cmp_gt_i32_e64 s[4:5], 4, v23
	v_add_u32_e32 v24, 0x8000, v20
	v_lshlrev_b32_e32 v23, 12, v23
	v_mov_b64_e32 v[20:21], s[6:7]
	s_movk_i32 s1, 0x1600
	v_mad_i64_i32 v[20:21], s[6:7], v24, s1, v[20:21]
	v_add_u32_e32 v75, v74, v23
	v_lshlrev_b32_e32 v22, 1, v22
	v_readlane_b32 s1, v254, 36
	v_readlane_b32 s10, v254, 45
	s_mov_b32 s11, s48
	s_branch .LBB0_1515

; #define LAS __attribute__((address_space(3)))
; __device__ __forceinline__ int ltid() { return launder((int)threadIdx.x); }
; template <class Epi, class Pre>
; __device__ __forceinline__ void meta_gemm(const bf16_t* __restrict__ A, int lda, const bf16_t* __restrict__ Bt, int ldb, int N, int K, Epi& epi, Pre pre) {
;   const int tid = ltid(), wid = tid >> 6, lane = tid & 63, fr = lane & 15, fq = lane >> 4;
;   LAS float* part = (LAS float*)lds_raw;
;   const int nunits = N / 64, ks = K / 8;
;   for (int u = blockIdx.x; u < nunits; u += gridDim.x) {
;     const int cb = (u >> 2) * 256 + (u & 3) * 32;
;     f32x4 acc[2][2];
; #pragma unroll
;     for (int bj = 0; bj < 2; ++bj)
; #pragma unroll
;       for (int n = 0; n < 2; ++n) acc[bj][n] = (f32x4){0.f, 0.f, 0.f, 0.f};
;     const bf16_t* ap = A + (size_t)(NREAL + fr) * lda + wid * ks + fq * 8;
;     const bf16_t* bp = Bt + (size_t)(cb + fr) * ldb + wid * ks + fq * 8;
; __global__ void __launch_bounds__(512) mega(Params P) {
;     ...
;     if (EN & 256) { EpiResid e; e.H = H; gemm_phase((const bf16_t*)(ws + WS_ACT), DFF, (const bf16_t*)(ws + WS_WDN) + (size_t)l * 1024 * DFF, DFF, NREAL, 1024, DFF, e); }
.Lgb_done_6:
.LBB0_1544:
	s_or_b64 exec, exec, s[4:5]
	v_readlane_b32 s0, v254, 54
	v_readlane_b32 s1, v254, 55
	s_mul_i32 s0, s0, 0x580000
	v_readlane_b32 s1, v253, 49
	s_add_u32 s6, s1, s0
	v_readlane_b32 s1, v253, 50
	s_addc_u32 s7, s1, 0
	v_mov_b32_e32 v2, v155
	s_and_b64 vcc, exec, s[2:3]
	s_barrier
	s_cbranch_vccnz .LBB0_1549
	v_and_b32_e32 v0, 15, v2
	v_or_b32_e32 v8, 0x8000, v0
	v_ashrrev_i32_e32 v10, 6, v2
	s_movk_i32 s1, 0x160
	v_mul_u32_u24_e32 v3, 0xb00, v8
	v_readlane_b32 s2, v254, 24
	v_mul_lo_u32 v6, v10, s1
	v_lshlrev_b32_e32 v4, 1, v3
	v_mov_b32_e32 v5, v1
	v_readlane_b32 s3, v254, 25
	v_ashrrev_i32_e32 v7, 31, v6
	v_lshlrev_b64 v[6:7], 1, v[6:7]
	v_lshl_add_u64 v[4:5], s[2:3], 0, v[4:5]
	v_and_b32_e32 v9, 63, v2
	v_lshl_add_u64 v[4:5], v[4:5], 0, v[6:7]
	v_and_b32_e32 v2, 48, v2
	v_mov_b32_e32 v3, v1
	v_lshl_add_u64 v[22:23], v[4:5], 0, v[2:3]
	v_lshl_add_u64 v[4:5], s[6:7], 0, v[6:7]
	v_lshl_add_u64 v[24:25], v[4:5], 0, v[2:3]
	v_lshl_add_u32 v4, v10, 4, v8
	v_ashrrev_i32_e32 v5, 31, v4
	v_readlane_b32 s4, v253, 60
	v_lshlrev_b64 v[4:5], 12, v[4:5]
	v_readlane_b32 s5, v253, 61
	v_lshl_add_u32 v42, v9, 2, 0
	v_lshlrev_b32_e32 v6, 12, v10
	v_lshl_add_u64 v[4:5], s[4:5], 0, v[4:5]
	v_cmp_gt_i32_e64 s[2:3], 4, v10
	v_lshl_add_u64 v[26:27], v[4:5], 0, v[2:3]
	v_add_u32_e32 v43, v42, v6
	v_readlane_b32 s1, v254, 36
	v_readlane_b32 s10, v254, 45
	s_mov_b32 s11, s48
	s_branch .LBB0_1547
